# v44 plus gmlp W-staging loads batched, GEMM K-loop header 64-byte aligned, attention epilogue gain loads pipelined
# speedup vs baseline: 1.0093x; 1.0093x over previous
; __device__ __forceinline__ void attn_unit(LAS unsigned char* lds, const bf16* Q, const bf16* K, const bf16* KV, bf16* Y, const float* gout, int b, int h, int qb, const int tid) {
;     ...
;     const float l = l_run + __shfl_xor(l_run, 32), inv = 1.0f / l;
;     float ss = 0.f;
; #pragma unroll
;     for (int d = 0; d < 4; ++d)
; #pragma unroll
;         for (int r = 0; r < 16; ++r) { o[d][r] *= inv; ss += o[d][r] * o[d][r]; }
;     ss += __shfl_xor(ss, 32);
;     const float rn = 1.0f / sqrtf(ss * (1.0f / VD) + EPS);
.LBB0_25:
	ds_bpermute_b32 v1, v230, v207
	s_waitcnt lgkmcnt(0)
	s_barrier
	global_load_dwordx4 v[80:83], v[196:197], off
	global_load_dwordx4 v[138:141], v[196:197], off offset:32
	global_load_dwordx4 v[142:145], v[196:197], off offset:64
	global_load_dwordx4 v[146:149], v[196:197], off offset:96
	global_load_dwordx4 v[150:153], v[196:197], off offset:128
	global_load_dwordx4 v[154:157], v[196:197], off offset:160
	global_load_dwordx4 v[158:161], v[196:197], off offset:192
	v_add_f32_e32 v1, v207, v1
	v_div_scale_f32 v2, s[4:5], v1, v1, 1.0
	v_rcp_f32_e32 v3, v2
	v_div_scale_f32 v4, vcc, 1.0, v1, 1.0
	s_add_i32 s0, s0, 1
	v_fma_f32 v5, -v2, v3, 1.0
	v_fmac_f32_e32 v3, v5, v3
	v_mul_f32_e32 v5, v4, v3
	v_fma_f32 v6, -v2, v5, v4
	v_fmac_f32_e32 v5, v6, v3
	v_fma_f32 v2, -v2, v5, v4
	v_div_fmas_f32 v2, v2, v3, v5
	v_div_fixup_f32 v8, v2, v1, 1.0
	v_pk_mul_f32 v[64:65], v[64:65], v[8:9] op_sel_hi:[1,0]
	v_pk_mul_f32 v[66:67], v[66:67], v[8:9] op_sel_hi:[1,0]
	v_pk_mul_f32 v[92:93], v[64:65], v[64:65]
	v_pk_mul_f32 v[90:91], v[66:67], v[66:67]
	v_add_f32_e32 v1, v92, v93
	v_pk_mul_f32 v[68:69], v[68:69], v[8:9] op_sel_hi:[1,0]
	v_add_f32_e32 v1, v90, v1
	v_pk_mul_f32 v[96:97], v[68:69], v[68:69]
	v_add_f32_e32 v1, v91, v1
	v_pk_mul_f32 v[70:71], v[70:71], v[8:9] op_sel_hi:[1,0]
	v_add_f32_e32 v1, v96, v1
	v_pk_mul_f32 v[94:95], v[70:71], v[70:71]
	v_add_f32_e32 v1, v97, v1
	v_pk_mul_f32 v[72:73], v[72:73], v[8:9] op_sel_hi:[1,0]
	v_add_f32_e32 v1, v94, v1
	v_pk_mul_f32 v[100:101], v[72:73], v[72:73]
	v_add_f32_e32 v1, v95, v1
	v_pk_mul_f32 v[74:75], v[74:75], v[8:9] op_sel_hi:[1,0]
	v_add_f32_e32 v1, v100, v1
	v_pk_mul_f32 v[98:99], v[74:75], v[74:75]
	v_add_f32_e32 v1, v101, v1
	v_pk_mul_f32 v[76:77], v[76:77], v[8:9] op_sel_hi:[1,0]
	v_add_f32_e32 v1, v98, v1
	v_pk_mul_f32 v[104:105], v[76:77], v[76:77]
	v_add_f32_e32 v1, v99, v1
	v_pk_mul_f32 v[78:79], v[78:79], v[8:9] op_sel_hi:[1,0]
	v_add_f32_e32 v1, v104, v1
	v_pk_mul_f32 v[102:103], v[78:79], v[78:79]
	v_add_f32_e32 v1, v105, v1
	v_pk_mul_f32 v[108:109], v[48:49], v[8:9] op_sel_hi:[1,0]
	v_add_f32_e32 v1, v102, v1
	v_pk_mul_f32 v[110:111], v[108:109], v[108:109]
	v_add_f32_e32 v1, v103, v1
	v_pk_mul_f32 v[50:51], v[50:51], v[8:9] op_sel_hi:[1,0]
	v_add_f32_e32 v1, v110, v1
	v_pk_mul_f32 v[106:107], v[50:51], v[50:51]
	v_add_f32_e32 v1, v111, v1
	v_pk_mul_f32 v[52:53], v[52:53], v[8:9] op_sel_hi:[1,0]
	v_add_f32_e32 v1, v106, v1
	v_pk_mul_f32 v[118:119], v[52:53], v[52:53]
	v_add_f32_e32 v1, v107, v1
	v_pk_mul_f32 v[54:55], v[54:55], v[8:9] op_sel_hi:[1,0]
	v_add_f32_e32 v1, v118, v1
	v_pk_mul_f32 v[116:117], v[54:55], v[54:55]
	v_add_f32_e32 v1, v119, v1
	v_pk_mul_f32 v[56:57], v[56:57], v[8:9] op_sel_hi:[1,0]
	v_add_f32_e32 v1, v116, v1
	v_pk_mul_f32 v[122:123], v[56:57], v[56:57]
	v_add_f32_e32 v1, v117, v1
	v_pk_mul_f32 v[58:59], v[58:59], v[8:9] op_sel_hi:[1,0]
	v_add_f32_e32 v1, v122, v1
	v_pk_mul_f32 v[120:121], v[58:59], v[58:59]
	v_add_f32_e32 v1, v123, v1
	v_pk_mul_f32 v[60:61], v[60:61], v[8:9] op_sel_hi:[1,0]
	v_add_f32_e32 v1, v120, v1
	v_pk_mul_f32 v[126:127], v[60:61], v[60:61]
	v_add_f32_e32 v1, v121, v1
	v_pk_mul_f32 v[62:63], v[62:63], v[8:9] op_sel_hi:[1,0]
	v_add_f32_e32 v1, v126, v1
	v_pk_mul_f32 v[124:125], v[62:63], v[62:63]
	v_add_f32_e32 v1, v127, v1
	v_pk_mul_f32 v[130:131], v[32:33], v[8:9] op_sel_hi:[1,0]
	v_add_f32_e32 v1, v124, v1
	v_pk_mul_f32 v[132:133], v[130:131], v[130:131]
	v_add_f32_e32 v1, v125, v1
	v_pk_mul_f32 v[48:49], v[34:35], v[8:9] op_sel_hi:[1,0]
	v_add_f32_e32 v1, v132, v1
	v_pk_mul_f32 v[128:129], v[48:49], v[48:49]
	v_add_f32_e32 v1, v133, v1
	v_pk_mul_f32 v[36:37], v[36:37], v[8:9] op_sel_hi:[1,0]
	v_add_f32_e32 v1, v128, v1
	v_pk_mul_f32 v[134:135], v[36:37], v[36:37]
	v_add_f32_e32 v1, v129, v1
	v_pk_mul_f32 v[32:33], v[38:39], v[8:9] op_sel_hi:[1,0]
	v_add_f32_e32 v1, v134, v1
	v_pk_mul_f32 v[38:39], v[32:33], v[32:33]
	v_add_f32_e32 v1, v135, v1
	v_pk_mul_f32 v[34:35], v[40:41], v[8:9] op_sel_hi:[1,0]
	v_add_f32_e32 v1, v38, v1
	v_pk_mul_f32 v[40:41], v[34:35], v[34:35]
	v_add_f32_e32 v1, v39, v1
	v_pk_mul_f32 v[2:3], v[28:29], v[8:9] op_sel_hi:[1,0]
	v_pk_mul_f32 v[28:29], v[42:43], v[8:9] op_sel_hi:[1,0]
	v_add_f32_e32 v1, v40, v1
	v_pk_mul_f32 v[42:43], v[28:29], v[28:29]
	v_add_f32_e32 v1, v41, v1
	v_pk_mul_f32 v[4:5], v[30:31], v[8:9] op_sel_hi:[1,0]
	v_pk_mul_f32 v[30:31], v[44:45], v[8:9] op_sel_hi:[1,0]
	v_add_f32_e32 v1, v42, v1
	v_pk_mul_f32 v[44:45], v[30:31], v[30:31]
	v_add_f32_e32 v1, v43, v1
	v_pk_mul_f32 v[6:7], v[26:27], v[8:9] op_sel_hi:[1,0]
	v_pk_mul_f32 v[26:27], v[46:47], v[8:9] op_sel_hi:[1,0]
	v_add_f32_e32 v1, v44, v1
	v_pk_mul_f32 v[46:47], v[26:27], v[26:27]
	v_add_f32_e32 v1, v45, v1
	v_pk_mul_f32 v[16:17], v[16:17], v[8:9] op_sel_hi:[1,0]
	v_add_f32_e32 v1, v46, v1
	v_pk_mul_f32 v[136:137], v[16:17], v[16:17]
	v_add_f32_e32 v1, v47, v1
	v_pk_mul_f32 v[14:15], v[18:19], v[8:9] op_sel_hi:[1,0]
	v_add_f32_e32 v1, v136, v1
	v_pk_mul_f32 v[18:19], v[14:15], v[14:15]
	v_add_f32_e32 v1, v137, v1
	v_pk_mul_f32 v[12:13], v[20:21], v[8:9] op_sel_hi:[1,0]
	v_add_f32_e32 v1, v18, v1
	v_pk_mul_f32 v[20:21], v[12:13], v[12:13]
	v_add_f32_e32 v1, v19, v1
	v_pk_mul_f32 v[10:11], v[22:23], v[8:9] op_sel_hi:[1,0]
	v_add_f32_e32 v1, v20, v1
	v_pk_mul_f32 v[22:23], v[10:11], v[10:11]
	v_add_f32_e32 v1, v21, v1
	v_pk_mul_f32 v[8:9], v[24:25], v[8:9] op_sel_hi:[1,0]
	v_add_f32_e32 v1, v22, v1
	v_pk_mul_f32 v[24:25], v[8:9], v[8:9]
	v_add_f32_e32 v1, v23, v1
	v_add_f32_e32 v1, v24, v1
	v_pk_mul_f32 v[84:85], v[6:7], v[6:7]
	v_add_f32_e32 v1, v25, v1
	v_add_f32_e32 v1, v84, v1
	v_pk_mul_f32 v[86:87], v[2:3], v[2:3]
	v_add_f32_e32 v1, v85, v1
	v_add_f32_e32 v1, v86, v1
	v_pk_mul_f32 v[88:89], v[4:5], v[4:5]
	v_add_f32_e32 v1, v87, v1
	v_add_f32_e32 v1, v88, v1
	v_add_f32_e32 v1, v89, v1
	ds_bpermute_b32 v18, v230, v1
	s_cmp_eq_u32 s0, 4
	s_waitcnt lgkmcnt(0)
; __device__ __forceinline__ unsigned cvt_pk_bf16(float lo, float hi) { f32x2 v = {lo, hi}; bf16x2_t b = __builtin_convertvector(v, bf16x2_t); return __builtin_bit_cast(unsigned, b); }
; __device__ __forceinline__ void attn_unit(LAS unsigned char* lds, const bf16* Q, const bf16* K, const bf16* KV, bf16* Y, const float* gout, int b, int h, int qb, const int tid) {
;     ...
;     const float rn = 1.0f / sqrtf(ss * (1.0f / VD) + EPS);
;     bf16* yp = Y + (tok0 + qrow) * DM + 1024 + h * VD + 4 * hi; const float* gp = gout + h * VD + 4 * hi;
; #pragma unroll
;     for (int d = 0; d < 4; ++d)
; #pragma unroll
;         for (int r4 = 0; r4 < 4; ++r4) { const f32x4 g = *(const f32x4*)(gp + 32 * d + 8 * r4); u32x2 w;
;             w.x = cvt_pk_bf16(o[d][4 * r4] * rn * g.x, o[d][4 * r4 + 1] * rn * g.y); w.y = cvt_pk_bf16(o[d][4 * r4 + 2] * rn * g.z, o[d][4 * r4 + 3] * rn * g.w);
;             *(u32x2*)(yp + 32 * d + 8 * r4) = w; }
	v_add_f32_e32 v1, v1, v18
	v_fmamk_f32 v1, v1, 0x3c000000, v214
	v_mul_f32_e32 v18, 0x4f800000, v1
	v_cmp_gt_f32_e32 vcc, s33, v1
	s_nop 1
	v_cndmask_b32_e32 v1, v1, v18, vcc
	v_sqrt_f32_e32 v18, v1
	s_nop 0
	v_add_u32_e32 v19, -1, v18
	v_fma_f32 v20, -v19, v18, v1
	v_cmp_ge_f32_e64 s[4:5], 0, v20
	v_add_u32_e32 v20, 1, v18
	s_nop 0
	v_cndmask_b32_e64 v19, v18, v19, s[4:5]
	v_fma_f32 v18, -v20, v18, v1
	v_cmp_lt_f32_e64 s[4:5], 0, v18
	s_nop 1
	v_cndmask_b32_e64 v18, v19, v20, s[4:5]
	v_mul_f32_e32 v19, 0x37800000, v18
	v_cndmask_b32_e32 v18, v18, v19, vcc
	v_cmp_class_f32_e32 vcc, v1, v215
	s_nop 1
	v_cndmask_b32_e32 v1, v18, v1, vcc
	v_div_scale_f32 v20, s[4:5], v1, v1, 1.0
	v_rcp_f32_e32 v21, v20
	v_lshlrev_b64 v[18:19], 12, v[204:205]
	v_lshl_add_u64 v[22:23], v[198:199], 0, v[18:19]
	v_fma_f32 v18, -v20, v21, 1.0
	v_fmac_f32_e32 v21, v18, v21
	v_div_scale_f32 v18, vcc, 1.0, v1, 1.0
	v_mul_f32_e32 v19, v18, v21
	v_fma_f32 v24, -v20, v19, v18
	v_fmac_f32_e32 v19, v24, v21
	v_fma_f32 v18, -v20, v19, v18
	v_div_fmas_f32 v18, v18, v21, v19
	v_div_fixup_f32 v24, v18, v1, 1.0
	v_pk_mul_f32 v[18:19], v[64:65], v[24:25] op_sel_hi:[1,0]
	v_pk_mul_f32 v[20:21], v[66:67], v[24:25] op_sel_hi:[1,0]
	s_waitcnt vmcnt(0)
	v_pk_mul_f32 v[18:19], v[80:81], v[18:19]
	v_pk_mul_f32 v[20:21], v[82:83], v[20:21]
	v_cvt_pk_bf16_f32 v18, v18, v19
	v_cvt_pk_bf16_f32 v19, v20, v21
	global_store_dwordx2 v[22:23], v[18:19], off offset:2048
	v_pk_mul_f32 v[38:39], v[68:69], v[24:25] op_sel_hi:[1,0]
	v_pk_mul_f32 v[40:41], v[70:71], v[24:25] op_sel_hi:[1,0]
	v_pk_mul_f32 v[36:37], v[36:37], v[24:25] op_sel_hi:[1,0]
	v_pk_mul_f32 v[32:33], v[32:33], v[24:25] op_sel_hi:[1,0]
	v_pk_mul_f32 v[28:29], v[28:29], v[24:25] op_sel_hi:[1,0]
	v_pk_mul_f32 v[26:27], v[26:27], v[24:25] op_sel_hi:[1,0]
	v_pk_mul_f32 v[16:17], v[16:17], v[24:25] op_sel_hi:[1,0]
	v_pk_mul_f32 v[14:15], v[14:15], v[24:25] op_sel_hi:[1,0]
	v_pk_mul_f32 v[12:13], v[12:13], v[24:25] op_sel_hi:[1,0]
	v_pk_mul_f32 v[10:11], v[10:11], v[24:25] op_sel_hi:[1,0]
	v_pk_mul_f32 v[8:9], v[8:9], v[24:25] op_sel_hi:[1,0]
	v_pk_mul_f32 v[6:7], v[6:7], v[24:25] op_sel_hi:[1,0]
	v_pk_mul_f32 v[2:3], v[2:3], v[24:25] op_sel_hi:[1,0]
	v_pk_mul_f32 v[4:5], v[4:5], v[24:25] op_sel_hi:[1,0]
	v_pk_mul_f32 v[18:19], v[138:139], v[38:39]
	v_pk_mul_f32 v[20:21], v[140:141], v[40:41]
	v_cvt_pk_bf16_f32 v18, v18, v19
	v_cvt_pk_bf16_f32 v19, v20, v21
	global_store_dwordx2 v[22:23], v[18:19], off offset:2064
	global_load_dwordx4 v[138:141], v[196:197], off offset:224
	v_pk_mul_f32 v[38:39], v[72:73], v[24:25] op_sel_hi:[1,0]
	v_pk_mul_f32 v[40:41], v[74:75], v[24:25] op_sel_hi:[1,0]
	v_pk_mul_f32 v[18:19], v[142:143], v[38:39]
	v_pk_mul_f32 v[20:21], v[144:145], v[40:41]
	v_cvt_pk_bf16_f32 v18, v18, v19
	v_cvt_pk_bf16_f32 v19, v20, v21
	global_store_dwordx2 v[22:23], v[18:19], off offset:2080
	global_load_dwordx4 v[142:145], v[196:197], off offset:256
	v_pk_mul_f32 v[38:39], v[76:77], v[24:25] op_sel_hi:[1,0]
	v_pk_mul_f32 v[40:41], v[78:79], v[24:25] op_sel_hi:[1,0]
	v_pk_mul_f32 v[18:19], v[146:147], v[38:39]
	v_pk_mul_f32 v[20:21], v[148:149], v[40:41]
	v_cvt_pk_bf16_f32 v18, v18, v19
	v_cvt_pk_bf16_f32 v19, v20, v21
	global_store_dwordx2 v[22:23], v[18:19], off offset:2096
	global_load_dwordx4 v[146:149], v[196:197], off offset:288
	v_pk_mul_f32 v[38:39], v[108:109], v[24:25] op_sel_hi:[1,0]
	v_pk_mul_f32 v[40:41], v[50:51], v[24:25] op_sel_hi:[1,0]
	v_pk_mul_f32 v[18:19], v[150:151], v[38:39]
	v_pk_mul_f32 v[20:21], v[152:153], v[40:41]
	v_cvt_pk_bf16_f32 v18, v18, v19
	v_cvt_pk_bf16_f32 v19, v20, v21
	global_store_dwordx2 v[22:23], v[18:19], off offset:2112
	global_load_dwordx4 v[150:153], v[196:197], off offset:320
	v_pk_mul_f32 v[38:39], v[52:53], v[24:25] op_sel_hi:[1,0]
	v_pk_mul_f32 v[40:41], v[54:55], v[24:25] op_sel_hi:[1,0]
	v_pk_mul_f32 v[18:19], v[154:155], v[38:39]
	v_pk_mul_f32 v[20:21], v[156:157], v[40:41]
	v_cvt_pk_bf16_f32 v18, v18, v19
	v_cvt_pk_bf16_f32 v19, v20, v21
	global_store_dwordx2 v[22:23], v[18:19], off offset:2128
	global_load_dwordx4 v[154:157], v[196:197], off offset:352
	v_pk_mul_f32 v[38:39], v[56:57], v[24:25] op_sel_hi:[1,0]
	v_pk_mul_f32 v[40:41], v[58:59], v[24:25] op_sel_hi:[1,0]
	v_pk_mul_f32 v[18:19], v[158:159], v[38:39]
	v_pk_mul_f32 v[20:21], v[160:161], v[40:41]
	v_cvt_pk_bf16_f32 v18, v18, v19
	v_cvt_pk_bf16_f32 v19, v20, v21
	global_store_dwordx2 v[22:23], v[18:19], off offset:2144
	global_load_dwordx4 v[158:161], v[196:197], off offset:384
	v_pk_mul_f32 v[38:39], v[60:61], v[24:25] op_sel_hi:[1,0]
	v_pk_mul_f32 v[40:41], v[62:63], v[24:25] op_sel_hi:[1,0]
	s_waitcnt vmcnt(10)
; __device__ __forceinline__ unsigned cvt_pk_bf16(float lo, float hi) { f32x2 v = {lo, hi}; bf16x2_t b = __builtin_convertvector(v, bf16x2_t); return __builtin_bit_cast(unsigned, b); }
; __device__ __forceinline__ void attn_unit(LAS unsigned char* lds, const bf16* Q, const bf16* K, const bf16* KV, bf16* Y, const float* gout, int b, int h, int qb, const int tid) {
;     ...
;     bf16* yp = Y + (tok0 + qrow) * DM + 1024 + h * VD + 4 * hi; const float* gp = gout + h * VD + 4 * hi;
; #pragma unroll
;     for (int d = 0; d < 4; ++d)
; #pragma unroll
;         for (int r4 = 0; r4 < 4; ++r4) { const f32x4 g = *(const f32x4*)(gp + 32 * d + 8 * r4); u32x2 w;
;             w.x = cvt_pk_bf16(o[d][4 * r4] * rn * g.x, o[d][4 * r4 + 1] * rn * g.y); w.y = cvt_pk_bf16(o[d][4 * r4 + 2] * rn * g.z, o[d][4 * r4 + 3] * rn * g.w);
;             *(u32x2*)(yp + 32 * d + 8 * r4) = w; }
	v_pk_mul_f32 v[18:19], v[138:139], v[38:39]
	v_pk_mul_f32 v[20:21], v[140:141], v[40:41]
	v_cvt_pk_bf16_f32 v18, v18, v19
	v_cvt_pk_bf16_f32 v19, v20, v21
	global_store_dwordx2 v[22:23], v[18:19], off offset:2160
	v_pk_mul_f32 v[38:39], v[130:131], v[24:25] op_sel_hi:[1,0]
	v_pk_mul_f32 v[40:41], v[48:49], v[24:25] op_sel_hi:[1,0]
	s_waitcnt vmcnt(9)
	v_pk_mul_f32 v[18:19], v[142:143], v[38:39]
	v_pk_mul_f32 v[20:21], v[144:145], v[40:41]
	v_cvt_pk_bf16_f32 v18, v18, v19
	v_cvt_pk_bf16_f32 v19, v20, v21
	global_store_dwordx2 v[22:23], v[18:19], off offset:2176
	s_waitcnt vmcnt(8)
	v_pk_mul_f32 v[18:19], v[146:147], v[36:37]
	v_pk_mul_f32 v[20:21], v[148:149], v[32:33]
	v_cvt_pk_bf16_f32 v18, v18, v19
	v_cvt_pk_bf16_f32 v19, v20, v21
	global_store_dwordx2 v[22:23], v[18:19], off offset:2192
	v_pk_mul_f32 v[32:33], v[34:35], v[24:25] op_sel_hi:[1,0]
	s_waitcnt vmcnt(7)
	v_pk_mul_f32 v[20:21], v[152:153], v[28:29]
	v_pk_mul_f32 v[18:19], v[150:151], v[32:33]
	v_pk_mul_f32 v[28:29], v[30:31], v[24:25] op_sel_hi:[1,0]
	v_cvt_pk_bf16_f32 v18, v18, v19
	v_cvt_pk_bf16_f32 v19, v20, v21
	global_store_dwordx2 v[22:23], v[18:19], off offset:2208
	s_waitcnt vmcnt(6)
	v_pk_mul_f32 v[18:19], v[154:155], v[28:29]
	v_pk_mul_f32 v[20:21], v[156:157], v[26:27]
	v_cvt_pk_bf16_f32 v18, v18, v19
	v_cvt_pk_bf16_f32 v19, v20, v21
	global_store_dwordx2 v[22:23], v[18:19], off offset:2224
	s_waitcnt vmcnt(5)
	v_pk_mul_f32 v[16:17], v[158:159], v[16:17]
	v_pk_mul_f32 v[14:15], v[160:161], v[14:15]
	v_cvt_pk_bf16_f32 v16, v16, v17
	v_cvt_pk_bf16_f32 v17, v14, v15
	global_store_dwordx2 v[22:23], v[16:17], off offset:2240
	global_load_dwordx4 v[14:17], v[196:197], off offset:416
	s_waitcnt vmcnt(0)
	v_pk_mul_f32 v[12:13], v[14:15], v[12:13]
	v_pk_mul_f32 v[10:11], v[16:17], v[10:11]
	v_cvt_pk_bf16_f32 v12, v12, v13
	v_cvt_pk_bf16_f32 v13, v10, v11
	global_store_dwordx2 v[22:23], v[12:13], off offset:2256
	global_load_dwordx4 v[10:13], v[196:197], off offset:448
	s_waitcnt vmcnt(0)
	v_pk_mul_f32 v[8:9], v[10:11], v[8:9]
	v_pk_mul_f32 v[6:7], v[12:13], v[6:7]
	v_cvt_pk_bf16_f32 v8, v8, v9
	v_cvt_pk_bf16_f32 v9, v6, v7
	global_store_dwordx2 v[22:23], v[8:9], off offset:2272
	global_load_dwordx4 v[6:9], v[196:197], off offset:480
	s_waitcnt vmcnt(0)
	v_pk_mul_f32 v[2:3], v[6:7], v[2:3]
	v_pk_mul_f32 v[4:5], v[8:9], v[4:5]
	v_cvt_pk_bf16_f32 v2, v2, v3
	v_cvt_pk_bf16_f32 v3, v4, v5
	global_store_dwordx2 v[22:23], v[2:3], off offset:2288
	s_cbranch_scc1 .LBB0_23

; __device__ __forceinline__ unsigned cvt_pk_bf16(float lo, float hi) { f32x2 v = {lo, hi}; bf16x2_t b = __builtin_convertvector(v, bf16x2_t); return __builtin_bit_cast(unsigned, b); }
; #define LAS __attribute__((address_space(3)))
; __device__ __forceinline__ void gmlp_phase(LAS unsigned char* lds, const bf16* Z, const float* w_s, const float* b_s, const float* gout, const float* ssv, const float* gv, bf16* Y, int vcu, int G, const int tid) {
;     ...
;         if (g != gcur) {
;             gcur = g;
; #pragma unroll
;             for (int i = 0; i < 8; ++i) { const int p = tid + 512 * i, t = p >> 5, s = (p & 31) * 4; const f32x4 w = *(const f32x4*)(w_s + (size_t)g * 16384 + t * 128 + s);
;                 u32x2 o; o.x = cvt_pk_bf16(s <= t ? w.x : 0.f, s + 1 <= t ? w.y : 0.f); o.y = cvt_pk_bf16(s + 2 <= t ? w.z : 0.f, s + 3 <= t ? w.w : 0.f);
;                 *(LAS u32x2*)(lds + t * WP + s * 2) = o; }
.LBB0_461:
	s_and_b32 s11, s10, 7
	s_cmp_eq_u32 s11, s9
	s_waitcnt vmcnt(8)
	s_barrier
	s_cbranch_scc1 .LBB0_463
	s_lshl_b32 s0, s11, 16
	v_lshl_add_u64 v[18:19], v[58:59], 0, s[0:1]
	s_mov_b32 s9, s11
	v_lshl_add_u64 v[190:191], v[66:67], 2, v[18:19]
	global_load_dwordx4 v[190:193], v[190:191], off
	v_lshl_add_u64 v[194:195], v[68:69], 2, v[18:19]
	global_load_dwordx4 v[194:197], v[194:195], off
	v_lshl_add_u64 v[198:199], v[70:71], 2, v[18:19]
	global_load_dwordx4 v[198:201], v[198:199], off
	v_lshl_add_u64 v[202:203], v[72:73], 2, v[18:19]
	global_load_dwordx4 v[202:205], v[202:203], off
	v_lshl_add_u64 v[206:207], v[74:75], 2, v[18:19]
	global_load_dwordx4 v[206:209], v[206:207], off
	v_lshl_add_u64 v[224:225], v[76:77], 2, v[18:19]
	global_load_dwordx4 v[224:227], v[224:225], off
	v_lshl_add_u64 v[228:229], v[78:79], 2, v[18:19]
	global_load_dwordx4 v[228:231], v[228:229], off
	v_lshl_add_u64 v[232:233], v[80:81], 2, v[18:19]
	global_load_dwordx4 v[232:235], v[232:233], off
	s_waitcnt vmcnt(0)
	v_cndmask_b32_e64 v20, v190, 0, s[40:41]
	v_cndmask_b32_e64 v21, 0, v191, s[42:43]
	v_cvt_pk_bf16_f32 v20, v20, v21
	v_cndmask_b32_e64 v21, v192, 0, s[44:45]
	v_cndmask_b32_e64 v22, v193, 0, s[46:47]
	v_cvt_pk_bf16_f32 v21, v21, v22
	ds_write_b64 v111, v[20:21]
	v_cndmask_b32_e64 v20, v194, 0, s[48:49]
	v_cndmask_b32_e64 v21, 0, v195, s[50:51]
	v_cvt_pk_bf16_f32 v20, v20, v21
	v_cndmask_b32_e64 v21, v196, 0, s[52:53]
	v_cndmask_b32_e64 v22, v197, 0, s[54:55]
	v_cvt_pk_bf16_f32 v21, v21, v22
	ds_write_b64 v116, v[20:21]
	v_cndmask_b32_e64 v20, v198, 0, s[56:57]
	v_cndmask_b32_e64 v21, 0, v199, s[58:59]
	v_cvt_pk_bf16_f32 v20, v20, v21
	v_cndmask_b32_e64 v21, v200, 0, s[60:61]
	v_cndmask_b32_e64 v22, v201, 0, s[62:63]
	v_cvt_pk_bf16_f32 v21, v21, v22
	ds_write_b64 v117, v[20:21]
	v_cndmask_b32_e64 v20, v202, 0, s[64:65]
	v_cndmask_b32_e64 v21, 0, v203, s[66:67]
	v_cvt_pk_bf16_f32 v20, v20, v21
	v_cndmask_b32_e64 v21, v204, 0, s[68:69]
	v_cndmask_b32_e64 v22, v205, 0, s[70:71]
	v_cvt_pk_bf16_f32 v21, v21, v22
	ds_write_b64 v118, v[20:21]
	v_cndmask_b32_e64 v20, v206, 0, s[72:73]
	v_cndmask_b32_e64 v21, 0, v207, s[74:75]
	v_cvt_pk_bf16_f32 v20, v20, v21
	v_cndmask_b32_e64 v21, v208, 0, s[76:77]
	v_cndmask_b32_e64 v22, v209, 0, s[78:79]
	v_cvt_pk_bf16_f32 v21, v21, v22
	ds_write_b64 v119, v[20:21]
	v_cndmask_b32_e64 v20, v224, 0, s[80:81]
	v_cndmask_b32_e64 v21, 0, v225, s[82:83]
	v_cvt_pk_bf16_f32 v20, v20, v21
	v_cndmask_b32_e64 v21, v226, 0, s[84:85]
	v_cndmask_b32_e64 v22, v227, 0, s[86:87]
	v_cvt_pk_bf16_f32 v21, v21, v22
	ds_write_b64 v120, v[20:21]
	v_cndmask_b32_e64 v20, v228, 0, s[88:89]
	v_cndmask_b32_e64 v21, 0, v229, s[90:91]
	v_cvt_pk_bf16_f32 v20, v20, v21
	v_cndmask_b32_e64 v21, v230, 0, s[92:93]
	v_cndmask_b32_e64 v22, v231, 0, s[94:95]
	v_cvt_pk_bf16_f32 v21, v21, v22
	ds_write_b64 v121, v[20:21]
	v_cndmask_b32_e64 v18, v232, 0, s[96:97]
	v_cndmask_b32_e64 v19, 0, v233, s[98:99]
	v_cvt_pk_bf16_f32 v18, v18, v19
	v_cndmask_b32_e64 v19, v234, 0, s[4:5]
	v_cndmask_b32_e64 v20, v235, 0, s[6:7]
	v_cvt_pk_bf16_f32 v19, v19, v20
	ds_write_b64 v122, v[18:19]
